# plus prep deltanet row loop: gate parameters loaded once before the loop, no vmcnt waits in the row body, next row waited for only before it is copied (counted past the row's stores)
# speedup vs baseline: 1.0047x; 1.0047x over previous
; __device__ __forceinline__ void prep_phase(const Params& P, int l, LAS unsigned char* lds) {
;     ...
;         int r = gw;
;         u32x4 ch_[12]; bf16_t cga = 0, cgb = 0;
; #pragma unroll
;         for (int i = 0; i < 12; ++i) ch_[i] = z4;
;         if (r < M) DNP_LOAD(ch_, cga, cgb, r);
; #pragma unroll 1
;         while (r < M) {
;             const int rn_ = r + NGW;
;             u32x4 nh_[12]; bf16_t nga = 0, ngb = 0;
; #pragma unroll
;             for (int i = 0; i < 12; ++i) nh_[i] = z4;
;             if (rn_ < M) DNP_LOAD(nh_, nga, ngb, rn_);
;     ...
;                     const float xx = araw + P.in[21][(l * 2 + dir) * 8 + hd];
;                     float sp; if (xx > 15.f) sp = xx; else { const float e = __expf(xx); sp = (e < 1e-3f) ? e * (1.f - e * (0.5f - e * (1.f / 3.f))) : __logf(1.f + e); }
;                     const float gg = -__expf(P.in[20][(l * 2 + dir) * 8 + hd]) * sp;
.LBB0_204:
	s_or_b64 exec, exec, s[10:11]
	v_readlane_b32 s6, v250, 16
	v_readlane_b32 s7, v250, 17
	s_mov_b32 s7, s87
	v_writelane_b32 v250, s6, 16
	v_lshlrev_b32_e32 v237, 3, v234
	v_lshlrev_b32_e32 v240, 4, v234
	v_writelane_b32 v250, s7, 17
	s_and_saveexec_b64 s[24:25], s[4:5]
	s_cbranch_execz .LBB0_233
	v_and_b32_e32 v2, 48, v237
	v_readlane_b32 s4, v250, 16
	v_and_or_b32 v2, v226, 64, v2
	s_lshl_b32 s6, s4, 4
	v_and_b32_e32 v1, 7, v234
	v_lshlrev_b32_e32 v241, 2, v2
	v_and_b32_e32 v2, 8, v234
	v_or3_b32 v2, v2, s6, v1
	v_readlane_b32 s8, v252, 8
	v_lshlrev_b64 v[150:151], 2, v[2:3]
	v_readlane_b32 s16, v252, 16
	v_readlane_b32 s17, v252, 17
	v_readlane_b32 s18, v252, 18
	v_readlane_b32 s19, v252, 19
	v_ashrrev_i32_e32 v1, 31, v0
	v_lshl_add_u64 v[204:205], s[16:17], 0, v[150:151]
	v_lshl_add_u64 v[202:203], s[18:19], 0, v[150:151]
	global_load_dword v254, v[202:203], off
	global_load_dword v255, v[204:205], off
	v_lshlrev_b64 v[150:151], 8, v[0:1]
	s_movk_i32 s6, 0xf0
	v_readlane_b32 s3, v251, 33
	v_and_or_b32 v150, v240, s6, v150
	s_mov_b64 s[6:7], 0x30140000
	v_lshlrev_b64 v[208:209], 12, v[0:1]
	v_lshlrev_b64 v[210:211], 11, v[0:1]
	v_add_u32_e32 v1, s3, v235
	v_readlane_b32 s5, v250, 17
	v_and_b32_e32 v149, 15, v234
	v_lshl_add_u64 v[206:207], v[150:151], 0, s[6:7]
	v_mad_i64_i32 v[212:213], s[6:7], v1, s43, 0
	v_lshlrev_b32_e32 v2, 4, v236
	v_cmp_gt_u32_e64 s[4:5], 16, v236
	v_or_b32_e32 v208, v208, v148
	v_or_b32_e32 v210, v210, v148
	v_mad_i64_i32 v[214:215], s[6:7], v1, s43, v[2:3]
	v_lshl_or_b32 v212, v149, 1, v212
	s_mov_b64 s[16:17], 0
	v_readlane_b32 s9, v252, 9
	v_readlane_b32 s10, v252, 10
	v_readlane_b32 s11, v252, 11
	v_readlane_b32 s12, v252, 12
	v_readlane_b32 s13, v252, 13
	v_readlane_b32 s14, v252, 14
	v_readlane_b32 s15, v252, 15
	v_readlane_b32 s20, v252, 20
	v_readlane_b32 s21, v252, 21
	v_readlane_b32 s22, v252, 22
	v_readlane_b32 s23, v252, 23
	s_waitcnt vmcnt(0)
	s_branch .LBB0_209

; __device__ __forceinline__ float sigm(float x) { return __builtin_amdgcn_rcpf(1.f + __expf(-x)); }
; __device__ __forceinline__ void prep_phase(const Params& P, int l, LAS unsigned char* lds) {
;     ...
;                     float sp; if (xx > 15.f) sp = xx; else { const float e = __expf(xx); sp = (e < 1e-3f) ? e * (1.f - e * (0.5f - e * (1.f / 3.f))) : __logf(1.f + e); }
;                     const float gg = -__expf(P.in[20][(l * 2 + dir) * 8 + hd]) * sp;
;                     *(f32x4*)(DNS + ((size_t)r * 16 + dir * 8 + hd) * 4) = (f32x4){__expf(gg), sigm(braw), qkh, gg};
;                 }
;             }
; #pragma unroll
;             for (int i = 0; i < 12; ++i) ch_[i] = nh_[i];
;             cga = nga; cgb = ngb; r = rn_;
.LBB0_207:
	s_or_b64 exec, exec, s[10:11]
	v_mov_b32_e32 v101, v255
	v_lshlrev_b32_e32 v103, 16, v238
	v_mul_f32_e32 v103, 0xbfb8aa3b, v103
	v_exp_f32_e32 v103, v103
	v_readlane_b32 s6, v252, 2
	v_readlane_b32 s7, v252, 3
	v_add_f32_e32 v104, 1.0, v103
	v_mul_f32_e32 v101, 0x3fb8aa3b, v101
	v_exp_f32_e32 v101, v101
	s_nop 0
	v_mul_f32_e64 v103, v100, -v101
	v_mul_f32_e32 v100, 0x3fb8aa3b, v103
	v_exp_f32_e32 v100, v100
	v_rcp_f32_e32 v101, v104
	v_lshl_add_u64 v[104:105], s[6:7], 0, v[206:207]
	s_waitcnt lgkmcnt(0)
	global_store_dwordx4 v[104:105], v[100:103], off
.LBB0_208:
	s_or_b64 exec, exec, s[8:9]
	s_waitcnt vmcnt(8)
	v_readlane_b32 s6, v251, 40
	v_readlane_b32 s7, v251, 41
	v_mov_b32_e32 v239, v1
	v_mov_b32_e32 v238, v2
	v_lshl_add_u64 v[206:207], v[206:207], 0, s[6:7]
	v_readlane_b32 s6, v251, 42
	v_readlane_b32 s7, v251, 43
	v_mov_b32_e32 v140, v152
	v_mov_b32_e32 v141, v153
	v_lshl_add_u64 v[208:209], v[208:209], 0, s[6:7]
	v_readlane_b32 s6, v251, 44
	v_readlane_b32 s7, v251, 45
	v_mov_b32_e32 v142, v154
	v_mov_b32_e32 v143, v155
	v_lshl_add_u64 v[210:211], v[210:211], 0, s[6:7]
	v_readlane_b32 s6, v251, 31
	v_readlane_b32 s7, v251, 32
	v_mov_b32_e32 v144, v156
	v_mov_b32_e32 v145, v157
	v_lshl_add_u64 v[214:215], v[214:215], 0, s[6:7]
	v_lshl_add_u64 v[212:213], v[212:213], 0, s[6:7]
	v_mov_b32_e32 v146, v158
	v_mov_b32_e32 v147, v159
	v_mov_b32_e32 v136, v148
	v_mov_b32_e32 v137, v149
	v_mov_b32_e32 v138, v150
	v_mov_b32_e32 v139, v151
	v_mov_b32_e32 v128, v164
	v_mov_b32_e32 v129, v165
	v_mov_b32_e32 v130, v166
	v_mov_b32_e32 v131, v167
	v_mov_b32_e32 v132, v168
	v_mov_b32_e32 v133, v169
	v_mov_b32_e32 v134, v170
	v_mov_b32_e32 v135, v171
	v_mov_b32_e32 v124, v160
	v_mov_b32_e32 v125, v161
	v_mov_b32_e32 v126, v162
	v_mov_b32_e32 v127, v163
	v_mov_b32_e32 v116, v176
	v_mov_b32_e32 v117, v177
	v_mov_b32_e32 v118, v178
	v_mov_b32_e32 v119, v179
	v_mov_b32_e32 v120, v180
	v_mov_b32_e32 v121, v181
	v_mov_b32_e32 v122, v182
	v_mov_b32_e32 v123, v183
	v_mov_b32_e32 v112, v172
	v_mov_b32_e32 v113, v173
	v_mov_b32_e32 v114, v174
	v_mov_b32_e32 v115, v175
	v_mov_b32_e32 v104, v188
	v_mov_b32_e32 v105, v189
	v_mov_b32_e32 v106, v190
	v_mov_b32_e32 v107, v191
	v_mov_b32_e32 v108, v192
	v_mov_b32_e32 v109, v193
	v_mov_b32_e32 v110, v194
	v_mov_b32_e32 v111, v195
	v_mov_b32_e32 v100, v184
	v_mov_b32_e32 v101, v185
	s_waitcnt lgkmcnt(0)
	v_mov_b32_e32 v102, v186
	v_mov_b32_e32 v103, v187
	s_andn2_b64 exec, exec, s[16:17]
	s_cbranch_execz .LBB0_233

; __device__ __forceinline__ float silu(float x) { return x * sigm(x); }
; __device__ __forceinline__ void prep_phase(const Params& P, int l, LAS unsigned char* lds) {
;     ...
;             for (int which = 0; which < 2; ++which) {
;                 float xm[8], x0[8], xp[8]; unpack8(ch_[3 * which], xm); unpack8(ch_[3 * which + 1], x0); unpack8(ch_[3 * which + 2], xp);
;                 float y[8], ss = 0.f;
; #pragma unroll
;                 for (int e = 0; e < 8; ++e) { y[e] = silu(xm[e] * (which ? cwq[0][e] : cwk[0][e]) + x0[e] * (which ? cwq[1][e] : cwk[1][e]) + xp[e] * (which ? cwq[2][e] : cwk[2][e])); ss += y[e] * y[e]; }
;                 ss = row_sum16(ss);
;                 const float rn = __builtin_amdgcn_rsqf(ss + 1e-6f) * (which ? 0.08838834764831845f : 1.f);
; #pragma unroll
;                 for (int e = 0; e < 8; ++e) { if (which) qn[e] = y[e] * rn; else kn[e] = y[e] * rn; }
;             }
.LBB0_227:
	s_or_b64 exec, exec, s[18:19]
	v_and_b32_e32 v245, 0xffff0000, v146
	v_lshlrev_b32_e32 v244, 16, v146
	v_and_b32_e32 v217, 0xffff0000, v142
	v_lshlrev_b32_e32 v216, 16, v142
	v_pk_mul_f32 v[244:245], v[12:13], v[244:245]
	v_and_b32_e32 v247, 0xffff0000, v138
	v_lshlrev_b32_e32 v246, 16, v138
	v_pk_fma_f32 v[216:217], v[4:5], v[216:217], v[244:245]
	v_lshlrev_b32_e32 v146, 16, v139
	v_pk_fma_f32 v[216:217], v[20:21], v[246:247], v[216:217]
	v_lshlrev_b32_e32 v246, 16, v144
	v_mul_f32_e32 v138, 0xbfb8aa3b, v216
	v_exp_f32_e32 v138, v138
	v_mul_f32_e32 v142, 0xbfb8aa3b, v217
	v_exp_f32_e32 v142, v142
	v_and_b32_e32 v247, 0xffff0000, v144
	v_add_f32_e32 v138, 1.0, v138
	v_rcp_f32_e32 v244, v138
	v_add_f32_e32 v138, 1.0, v142
	v_rcp_f32_e32 v245, v138
	v_lshlrev_b32_e32 v142, 16, v147
	v_pk_mul_f32 v[246:247], v[16:17], v[246:247]
	v_lshlrev_b32_e32 v248, 16, v136
	v_pk_mul_f32 v[216:217], v[216:217], v[244:245]
	v_and_b32_e32 v245, 0xffff0000, v143
	v_lshlrev_b32_e32 v244, 16, v143
	v_and_b32_e32 v143, 0xffff0000, v147
	v_and_b32_e32 v147, 0xffff0000, v139
	v_pk_mul_f32 v[138:139], v[14:15], v[142:143]
	v_and_b32_e32 v249, 0xffff0000, v136
	v_pk_fma_f32 v[138:139], v[6:7], v[244:245], v[138:139]
	v_lshlrev_b32_e32 v244, 16, v140
	v_pk_fma_f32 v[138:139], v[22:23], v[146:147], v[138:139]
	v_and_b32_e32 v245, 0xffff0000, v140
	v_mul_f32_e32 v142, 0xbfb8aa3b, v138
	v_exp_f32_e32 v146, v142
	v_mul_f32_e32 v142, 0xbfb8aa3b, v139
	v_exp_f32_e32 v147, v142
	v_pk_fma_f32 v[244:245], v[8:9], v[244:245], v[246:247]
	v_add_f32_e32 v146, 1.0, v146
	v_pk_fma_f32 v[244:245], v[24:25], v[248:249], v[244:245]
	v_add_f32_e32 v147, 1.0, v147
	v_mul_f32_e32 v140, 0xbfb8aa3b, v245
	v_rcp_f32_e32 v146, v146
	v_rcp_f32_e32 v147, v147
	v_exp_f32_e32 v140, v140
	v_lshlrev_b32_e32 v144, 16, v137
	v_mul_f32_e32 v136, 0xbfb8aa3b, v244
	v_pk_mul_f32 v[146:147], v[138:139], v[146:147]
	v_add_f32_e32 v246, 1.0, v140
	v_lshlrev_b32_e32 v138, 16, v141
	v_and_b32_e32 v139, 0xffff0000, v141
	v_lshlrev_b32_e32 v140, 16, v145
	v_and_b32_e32 v141, 0xffff0000, v145
	v_pk_mul_f32 v[140:141], v[18:19], v[140:141]
	v_and_b32_e32 v145, 0xffff0000, v137
	v_pk_fma_f32 v[138:139], v[10:11], v[138:139], v[140:141]
	v_exp_f32_e32 v136, v136
	v_pk_fma_f32 v[138:139], v[26:27], v[144:145], v[138:139]
	v_pk_mul_f32 v[142:143], v[216:217], v[216:217]
	v_mul_f32_e32 v137, 0xbfb8aa3b, v138
	v_exp_f32_e32 v140, v137
	v_mul_f32_e32 v137, 0xbfb8aa3b, v139
	v_exp_f32_e32 v141, v137
	v_add_f32_e32 v136, 1.0, v136
	v_rcp_f32_e32 v136, v136
	v_rcp_f32_e32 v137, v246
	v_add_f32_e32 v140, 1.0, v140
	v_add_f32_e32 v141, 1.0, v141
	v_rcp_f32_e32 v140, v140
	v_rcp_f32_e32 v141, v141
	v_pk_mul_f32 v[136:137], v[244:245], v[136:137]
	v_pk_mul_f32 v[144:145], v[146:147], v[146:147]
	v_pk_mul_f32 v[244:245], v[136:137], v[136:137]
	v_pk_mul_f32 v[138:139], v[138:139], v[140:141]
	v_add_f32_e32 v244, v244, v245
	v_pk_mul_f32 v[140:141], v[138:139], v[138:139]
	v_and_b32_e32 v245, 0xffff0000, v132
	v_add_f32_e32 v140, v140, v244
	v_add_f32_e32 v140, v141, v140
	v_add_f32_e32 v140, v142, v140
	v_add_f32_e32 v140, v143, v140
	v_add_f32_e32 v140, v144, v140
	v_add_f32_e32 v140, v145, v140
	v_and_b32_e32 v143, 0xffff0000, v134
	v_lshlrev_b32_e32 v142, 16, v134
	v_add_f32_dpp v140, v140, v140 row_ror:8 row_mask:0xf bank_mask:0xf bound_ctrl:1
	v_and_b32_e32 v141, 0xffff0000, v130
	v_pk_mul_f32 v[142:143], v[36:37], v[142:143]
	v_add_f32_dpp v140, v140, v140 row_ror:4 row_mask:0xf bank_mask:0xf bound_ctrl:1
	v_and_b32_e32 v145, 0xffff0000, v126
	v_lshlrev_b32_e32 v144, 16, v126
	v_add_f32_dpp v140, v140, v140 row_ror:2 row_mask:0xf bank_mask:0xf bound_ctrl:1
	v_lshlrev_b32_e32 v246, 16, v124
	v_and_b32_e32 v247, 0xffff0000, v124
	v_add_f32_dpp v140, v140, v140 row_ror:1 row_mask:0xf bank_mask:0xf bound_ctrl:1
	v_add_f32_e32 v244, 0x358637bd, v140
	v_lshlrev_b32_e32 v140, 16, v130
	v_pk_fma_f32 v[140:141], v[28:29], v[140:141], v[142:143]
	v_readlane_b32 s8, v252, 2
	v_pk_fma_f32 v[140:141], v[44:45], v[144:145], v[140:141]
	v_lshlrev_b32_e32 v144, 16, v128
	v_mul_f32_e32 v126, 0xbfb8aa3b, v140
	v_exp_f32_e32 v130, v126
	v_mul_f32_e32 v126, 0xbfb8aa3b, v141
	v_exp_f32_e32 v134, v126
	v_rsq_f32_e32 v126, v244
	v_add_f32_e32 v130, 1.0, v130
	v_rcp_f32_e32 v142, v130
	v_add_f32_e32 v130, 1.0, v134
	v_rcp_f32_e32 v143, v130
	v_lshlrev_b32_e32 v130, 16, v135
	v_lshlrev_b32_e32 v134, 16, v127
	v_pk_mul_f32 v[136:137], v[136:137], v[126:127] op_sel_hi:[1,0]
	v_pk_mul_f32 v[140:141], v[140:141], v[142:143]
	v_and_b32_e32 v143, 0xffff0000, v131
	v_lshlrev_b32_e32 v142, 16, v131
	v_and_b32_e32 v131, 0xffff0000, v135
	v_pk_mul_f32 v[130:131], v[38:39], v[130:131]
	v_and_b32_e32 v135, 0xffff0000, v127
	v_pk_fma_f32 v[130:131], v[30:31], v[142:143], v[130:131]
	v_lshlrev_b32_e32 v244, 16, v132
	v_pk_fma_f32 v[130:131], v[46:47], v[134:135], v[130:131]
	v_and_b32_e32 v145, 0xffff0000, v128
	v_mul_f32_e32 v127, 0xbfb8aa3b, v130
	v_exp_f32_e32 v127, v127
	v_mul_f32_e32 v134, 0xbfb8aa3b, v131
	v_exp_f32_e32 v143, v134
	v_pk_mul_f32 v[244:245], v[40:41], v[244:245]
	v_add_f32_e32 v127, 1.0, v127
	v_rcp_f32_e32 v142, v127
	v_add_f32_e32 v127, 1.0, v143
	v_rcp_f32_e32 v143, v127
	v_pk_fma_f32 v[144:145], v[32:33], v[144:145], v[244:245]
	v_lshlrev_b32_e32 v128, 16, v129
	v_and_b32_e32 v129, 0xffff0000, v129
	v_pk_mul_f32 v[142:143], v[130:131], v[142:143]
	v_lshlrev_b32_e32 v130, 16, v133
	v_and_b32_e32 v131, 0xffff0000, v133
	v_pk_mul_f32 v[130:131], v[42:43], v[130:131]
	v_pk_fma_f32 v[144:145], v[48:49], v[246:247], v[144:145]
	v_lshlrev_b32_e32 v132, 16, v125
	v_and_b32_e32 v133, 0xffff0000, v125
; __device__ __forceinline__ float silu(float x) { return x * sigm(x); }
; __device__ __forceinline__ void prep_phase(const Params& P, int l, LAS unsigned char* lds) {
;     ...
;                 for (int e = 0; e < 8; ++e) { y[e] = silu(xm[e] * (which ? cwq[0][e] : cwk[0][e]) + x0[e] * (which ? cwq[1][e] : cwk[1][e]) + xp[e] * (which ? cwq[2][e] : cwk[2][e])); ss += y[e] * y[e]; }
;                 ss = row_sum16(ss);
;                 const float rn = __builtin_amdgcn_rsqf(ss + 1e-6f) * (which ? 0.08838834764831845f : 1.f);
; #pragma unroll
;                 for (int e = 0; e < 8; ++e) { if (which) qn[e] = y[e] * rn; else kn[e] = y[e] * rn; }
;             }
;             float qk = 0.f;
; #pragma unroll
;             for (int e = 0; e < 8; ++e) qk += qn[e] * kn[e];
;             qk = row_sum16(qk);
;             *(f32x4*)(DNK + (size_t)r * 512 + lane * 8) = (f32x4){kn[0], kn[1], kn[2], kn[3]}; *(f32x4*)(DNK + (size_t)r * 512 + lane * 8 + 4) = (f32x4){kn[4], kn[5], kn[6], kn[7]};
;             *(f32x4*)(DNQ + (size_t)r * 512 + lane * 8) = (f32x4){qn[0], qn[1], qn[2], qn[3]}; *(f32x4*)(DNQ + (size_t)r * 512 + lane * 8 + 4) = (f32x4){qn[4], qn[5], qn[6], qn[7]};
; #pragma unroll
;             for (int half = 0; half < 2; ++half) {
;                 const int cc = half * 512 + lane * 8;
;                 float xm[8], x0[8], xp[8]; unpack8(ch_[6 + 3 * half], xm); unpack8(ch_[6 + 3 * half + 1], x0); unpack8(ch_[6 + 3 * half + 2], xp);
;                 float y[8];
; #pragma unroll
;                 for (int e = 0; e < 8; ++e) y[e] = silu(xm[e] * cwv[half][0][e] + x0[e] * cwv[half][1][e] + xp[e] * cwv[half][2][e]);
;                 *(f32x4*)(DNV + (size_t)r * 1024 + cc) = (f32x4){y[0], y[1], y[2], y[3]}; *(f32x4*)(DNV + (size_t)r * 1024 + cc + 4) = (f32x4){y[4], y[5], y[6], y[7]};
	v_pk_fma_f32 v[128:129], v[34:35], v[128:129], v[130:131]
	v_mul_f32_e32 v127, 0xbfb8aa3b, v145
	v_pk_fma_f32 v[128:129], v[50:51], v[132:133], v[128:129]
	v_mul_f32_e32 v124, 0xbfb8aa3b, v144
	v_exp_f32_e32 v127, v127
	v_mul_f32_e32 v125, 0xbfb8aa3b, v128
	v_exp_f32_e32 v124, v124
	v_exp_f32_e32 v130, v125
	v_mul_f32_e32 v125, 0xbfb8aa3b, v129
	v_exp_f32_e32 v131, v125
	v_add_f32_e32 v127, 1.0, v127
	v_add_f32_e32 v124, 1.0, v124
	v_rcp_f32_e32 v125, v127
	v_add_f32_e32 v127, 1.0, v130
	v_rcp_f32_e32 v124, v124
	v_rcp_f32_e32 v130, v127
	v_add_f32_e32 v127, 1.0, v131
	v_rcp_f32_e32 v131, v127
	v_pk_mul_f32 v[144:145], v[144:145], v[124:125]
	v_pk_mul_f32 v[134:135], v[140:141], v[140:141]
	v_pk_mul_f32 v[124:125], v[144:145], v[144:145]
	v_pk_mul_f32 v[130:131], v[128:129], v[130:131]
	v_add_f32_e32 v124, v124, v125
	v_pk_mul_f32 v[128:129], v[130:131], v[130:131]
	v_pk_mul_f32 v[132:133], v[142:143], v[142:143]
	v_add_f32_e32 v124, v128, v124
	v_add_f32_e32 v124, v129, v124
	v_add_f32_e32 v124, v134, v124
	v_add_f32_e32 v124, v135, v124
	v_add_f32_e32 v124, v132, v124
	v_add_f32_e32 v124, v133, v124
	v_pk_mul_f32 v[138:139], v[138:139], v[126:127] op_sel_hi:[1,0]
	s_and_b64 s[6:7], exec, s[6:7]
	v_add_f32_dpp v124, v124, v124 row_ror:8 row_mask:0xf bank_mask:0xf bound_ctrl:1
	v_readlane_b32 s9, v252, 3
	s_or_b64 s[16:17], s[6:7], s[16:17]
	v_add_f32_dpp v124, v124, v124 row_ror:4 row_mask:0xf bank_mask:0xf bound_ctrl:1
	s_mov_b32 s6, 0x2bd40000
	s_nop 0
	v_add_f32_dpp v124, v124, v124 row_ror:2 row_mask:0xf bank_mask:0xf bound_ctrl:1
	s_nop 1
	v_add_f32_dpp v124, v124, v124 row_ror:1 row_mask:0xf bank_mask:0xf bound_ctrl:1
	v_add_f32_e32 v124, 0x358637bd, v124
	v_rsq_f32_e32 v128, v124
	v_pk_mul_f32 v[124:125], v[216:217], v[126:127] op_sel_hi:[1,0]
	v_pk_mul_f32 v[126:127], v[146:147], v[126:127] op_sel_hi:[1,0]
	v_mul_f32_e32 v134, 0x3db504f3, v128
	v_pk_mul_f32 v[128:129], v[144:145], v[134:135] op_sel_hi:[1,0]
	v_pk_mul_f32 v[132:133], v[140:141], v[134:135] op_sel_hi:[1,0]
	v_pk_mul_f32 v[140:141], v[136:137], v[128:129]
	v_pk_mul_f32 v[130:131], v[130:131], v[134:135] op_sel_hi:[1,0]
	v_add_f32_e32 v140, 0, v140
	v_pk_mul_f32 v[134:135], v[142:143], v[134:135] op_sel_hi:[1,0]
	v_add_f32_e32 v142, v141, v140
	v_pk_mul_f32 v[140:141], v[138:139], v[130:131]
	s_nop 0
	v_add_f32_e32 v140, v140, v142
	v_add_f32_e32 v142, v141, v140
	v_pk_mul_f32 v[140:141], v[124:125], v[132:133]
	s_nop 0
	v_add_f32_e32 v140, v140, v142
	v_add_f32_e32 v142, v141, v140
	v_pk_mul_f32 v[140:141], v[126:127], v[134:135]
	s_nop 0
	v_add_f32_e32 v140, v140, v142
	v_add_f32_e32 v140, v141, v140
	s_nop 1
	v_add_f32_dpp v140, v140, v140 row_ror:8 row_mask:0xf bank_mask:0xf bound_ctrl:1
	s_nop 1
	v_add_f32_dpp v140, v140, v140 row_ror:4 row_mask:0xf bank_mask:0xf bound_ctrl:1
	s_nop 1
	v_add_f32_dpp v144, v140, v140 row_ror:2 row_mask:0xf bank_mask:0xf bound_ctrl:1
	v_lshl_add_u64 v[140:141], s[8:9], 0, v[210:211]
	v_add_co_u32_e32 v142, vcc, s6, v140
	s_mov_b32 s6, 0x2ce40000
	s_nop 0
	v_addc_co_u32_e32 v143, vcc, 0, v141, vcc
	global_store_dwordx4 v[142:143], v[136:139], off
	global_store_dwordx4 v[142:143], v[124:127], off offset:16
	v_mov_b32_dpp v145, v144 row_ror:1 row_mask:0xf bank_mask:0xf bound_ctrl:1
	s_nop 0
	v_add_co_u32_e32 v124, vcc, s6, v140
	v_lshlrev_b32_e32 v126, 16, v116
	s_nop 0
	v_addc_co_u32_e32 v125, vcc, 0, v141, vcc
	global_store_dwordx4 v[124:125], v[128:131], off
	v_and_b32_e32 v127, 0xffff0000, v116
	global_store_dwordx4 v[124:125], v[132:135], off offset:16
	v_lshlrev_b32_e32 v128, 16, v120
	v_and_b32_e32 v129, 0xffff0000, v120
	v_pk_mul_f32 v[128:129], v[68:69], v[128:129]
	v_lshlrev_b32_e32 v130, 16, v112
	v_and_b32_e32 v131, 0xffff0000, v112
	v_pk_fma_f32 v[126:127], v[84:85], v[126:127], v[128:129]
	v_lshlrev_b32_e32 v120, 16, v121
	v_pk_fma_f32 v[126:127], v[76:77], v[130:131], v[126:127]
	v_and_b32_e32 v121, 0xffff0000, v121
	v_mul_f32_e32 v116, 0xbfb8aa3b, v127
	v_exp_f32_e32 v116, v116
	v_pk_mul_f32 v[120:121], v[70:71], v[120:121]
	v_lshlrev_b32_e32 v124, 16, v113
	v_and_b32_e32 v125, 0xffff0000, v113
	v_add_f32_e32 v128, 1.0, v116
	v_lshlrev_b32_e32 v116, 16, v117
	v_and_b32_e32 v117, 0xffff0000, v117
	v_pk_fma_f32 v[116:117], v[86:87], v[116:117], v[120:121]
	v_and_b32_e32 v129, 0xffff0000, v122
	v_pk_fma_f32 v[116:117], v[78:79], v[124:125], v[116:117]
	v_lshlrev_b32_e32 v124, 16, v118
	v_mul_f32_e32 v113, 0xbfb8aa3b, v116
	v_exp_f32_e32 v120, v113
	v_mul_f32_e32 v113, 0xbfb8aa3b, v117
	v_exp_f32_e32 v121, v113
	v_rcp_f32_e32 v113, v128
	v_lshlrev_b32_e32 v128, 16, v122
	v_and_b32_e32 v125, 0xffff0000, v118
	v_pk_mul_f32 v[128:129], v[56:57], v[128:129]
	v_lshlrev_b32_e32 v130, 16, v114
	v_and_b32_e32 v131, 0xffff0000, v114
	v_pk_fma_f32 v[124:125], v[92:93], v[124:125], v[128:129]
	v_lshlrev_b32_e32 v128, 16, v119
	v_pk_fma_f32 v[124:125], v[52:53], v[130:131], v[124:125]
	v_and_b32_e32 v129, 0xffff0000, v119
	v_mul_f32_e32 v118, 0xbfb8aa3b, v125
	v_mul_f32_e32 v114, 0xbfb8aa3b, v124
	v_exp_f32_e32 v122, v118
	v_exp_f32_e32 v114, v114
	v_mul_f32_e32 v112, 0xbfb8aa3b, v126
	v_exp_f32_e32 v112, v112
	v_add_f32_e32 v130, 1.0, v122
; __device__ __forceinline__ float bf1(bf16_t u) { return __uint_as_float(((unsigned)u) << 16); }
; __device__ __forceinline__ float sigm(float x) { return __builtin_amdgcn_rcpf(1.f + __expf(-x)); }
; __device__ __forceinline__ float silu(float x) { return x * sigm(x); }
; __device__ __forceinline__ void prep_phase(const Params& P, int l, LAS unsigned char* lds) {
;     ...
;                 float xm[8], x0[8], xp[8]; unpack8(ch_[6 + 3 * half], xm); unpack8(ch_[6 + 3 * half + 1], x0); unpack8(ch_[6 + 3 * half + 2], xp);
;                 float y[8];
; #pragma unroll
;                 for (int e = 0; e < 8; ++e) y[e] = silu(xm[e] * cwv[half][0][e] + x0[e] * cwv[half][1][e] + xp[e] * cwv[half][2][e]);
;                 *(f32x4*)(DNV + (size_t)r * 1024 + cc) = (f32x4){y[0], y[1], y[2], y[3]}; *(f32x4*)(DNV + (size_t)r * 1024 + cc + 4) = (f32x4){y[4], y[5], y[6], y[7]};
;             }
;             {
;                 const int hd = lane & 7, dir = (lane >> 3) & 1;
;                 const float qkh = __shfl(qk, 16 * (hd >> 1));
;                 if (lane < 16) {
;                     const float araw = bf1(cga), braw = bf1(cgb);
;                     const float xx = araw + P.in[21][(l * 2 + dir) * 8 + hd];
;                     float sp; if (xx > 15.f) sp = xx; else { const float e = __expf(xx); sp = (e < 1e-3f) ? e * (1.f - e * (0.5f - e * (1.f / 3.f))) : __logf(1.f + e); }
;                     const float gg = -__expf(P.in[20][(l * 2 + dir) * 8 + hd]) * sp;
;                     *(f32x4*)(DNS + ((size_t)r * 16 + dir * 8 + hd) * 4) = (f32x4){__expf(gg), sigm(braw), qkh, gg};
	v_lshlrev_b32_e32 v122, 16, v123
	v_and_b32_e32 v123, 0xffff0000, v123
	v_add_f32_e32 v114, 1.0, v114
	v_pk_mul_f32 v[122:123], v[58:59], v[122:123]
	v_rcp_f32_e32 v118, v114
	v_lshlrev_b32_e32 v114, 16, v115
	v_and_b32_e32 v115, 0xffff0000, v115
	v_pk_fma_f32 v[122:123], v[94:95], v[128:129], v[122:123]
	v_add_f32_e32 v120, 1.0, v120
	v_pk_fma_f32 v[122:123], v[54:55], v[114:115], v[122:123]
	v_add_f32_e32 v121, 1.0, v121
	v_mul_f32_e32 v114, 0xbfb8aa3b, v122
	v_exp_f32_e32 v114, v114
	v_mul_f32_e32 v115, 0xbfb8aa3b, v123
	v_exp_f32_e32 v115, v115
	v_rcp_f32_e32 v120, v120
	v_rcp_f32_e32 v121, v121
	v_add_f32_e32 v112, 1.0, v112
	v_rcp_f32_e32 v112, v112
	v_add_f32_e32 v114, 1.0, v114
	v_rcp_f32_e32 v119, v130
	v_rcp_f32_e32 v128, v114
	v_add_f32_e32 v114, 1.0, v115
	v_rcp_f32_e32 v129, v114
	v_pk_mul_f32 v[114:115], v[116:117], v[120:121]
	v_lshl_add_u64 v[116:117], s[8:9], 0, v[208:209]
	s_mov_b32 s6, 0x2df40000
	v_add_co_u32_e32 v116, vcc, s6, v116
	v_pk_mul_f32 v[112:113], v[126:127], v[112:113]
	s_nop 0
	v_addc_co_u32_e32 v117, vcc, 0, v117, vcc
	v_lshlrev_b32_e32 v120, 16, v108
	v_and_b32_e32 v121, 0xffff0000, v108
	global_store_dwordx4 v[116:117], v[112:115], off
	v_pk_mul_f32 v[120:121], v[72:73], v[120:121]
	v_lshlrev_b32_e32 v108, 16, v109
	v_pk_mul_f32 v[112:113], v[124:125], v[118:119]
	v_lshlrev_b32_e32 v118, 16, v104
	v_and_b32_e32 v119, 0xffff0000, v104
	v_pk_mul_f32 v[114:115], v[122:123], v[128:129]
	v_lshlrev_b32_e32 v122, 16, v100
	v_and_b32_e32 v123, 0xffff0000, v100
	v_pk_fma_f32 v[118:119], v[96:97], v[118:119], v[120:121]
	v_and_b32_e32 v109, 0xffff0000, v109
	v_pk_fma_f32 v[118:119], v[80:81], v[122:123], v[118:119]
	global_store_dwordx4 v[116:117], v[112:115], off offset:16
	v_mul_f32_e32 v104, 0xbfb8aa3b, v119
	v_exp_f32_e32 v104, v104
	v_pk_mul_f32 v[108:109], v[74:75], v[108:109]
	v_lshlrev_b32_e32 v112, 16, v101
	v_and_b32_e32 v113, 0xffff0000, v101
	v_add_f32_e32 v114, 1.0, v104
	v_lshlrev_b32_e32 v104, 16, v105
	v_and_b32_e32 v105, 0xffff0000, v105
	v_pk_fma_f32 v[104:105], v[98:99], v[104:105], v[108:109]
	v_and_b32_e32 v115, 0xffff0000, v110
	v_pk_fma_f32 v[108:109], v[82:83], v[112:113], v[104:105]
	v_lshlrev_b32_e32 v120, 16, v102
	v_mul_f32_e32 v101, 0xbfb8aa3b, v108
	v_exp_f32_e32 v104, v101
	v_mul_f32_e32 v101, 0xbfb8aa3b, v109
	v_exp_f32_e32 v105, v101
	v_rcp_f32_e32 v101, v114
	v_add_f32_e32 v104, 1.0, v104
	v_lshlrev_b32_e32 v114, 16, v110
	v_rcp_f32_e32 v112, v104
	v_add_f32_e32 v113, 1.0, v105
	v_lshlrev_b32_e32 v104, 16, v106
	v_and_b32_e32 v105, 0xffff0000, v106
	v_pk_mul_f32 v[114:115], v[60:61], v[114:115]
	v_and_b32_e32 v121, 0xffff0000, v102
	v_pk_fma_f32 v[104:105], v[88:89], v[104:105], v[114:115]
	v_mul_f32_e32 v100, 0xbfb8aa3b, v118
	v_pk_fma_f32 v[114:115], v[64:65], v[120:121], v[104:105]
	v_and_b32_e32 v105, 0xffff0000, v107
	v_mul_f32_e32 v104, 0xbfb8aa3b, v115
	v_mul_f32_e32 v102, 0xbfb8aa3b, v114
	v_exp_f32_e32 v104, v104
	v_exp_f32_e32 v102, v102
	v_lshlrev_b32_e32 v106, 16, v111
	v_exp_f32_e32 v100, v100
	v_add_f32_e32 v122, 1.0, v104
	v_lshlrev_b32_e32 v104, 16, v107
	v_and_b32_e32 v107, 0xffff0000, v111
	v_add_f32_e32 v102, 1.0, v102
	v_pk_mul_f32 v[106:107], v[62:63], v[106:107]
	v_rcp_f32_e32 v110, v102
	v_lshlrev_b32_e32 v102, 16, v103
	v_and_b32_e32 v103, 0xffff0000, v103
	v_pk_fma_f32 v[104:105], v[90:91], v[104:105], v[106:107]
	v_add_f32_e32 v100, 1.0, v100
	v_pk_fma_f32 v[120:121], v[66:67], v[102:103], v[104:105]
	v_rcp_f32_e32 v100, v100
	v_mul_f32_e32 v102, 0xbfb8aa3b, v120
	v_exp_f32_e32 v102, v102
	v_mul_f32_e32 v103, 0xbfb8aa3b, v121
	v_exp_f32_e32 v103, v103
	v_rcp_f32_e32 v113, v113
	v_add_f32_e32 v102, 1.0, v102
	v_rcp_f32_e32 v111, v122
	v_rcp_f32_e32 v122, v102
	v_add_f32_e32 v102, 1.0, v103
	v_pk_mul_f32 v[104:105], v[118:119], v[100:101]
	v_add_f32_e32 v100, v144, v145
	v_rcp_f32_e32 v123, v102
	ds_bpermute_b32 v102, v241, v100
	v_pk_mul_f32 v[106:107], v[108:109], v[112:113]
	global_store_dwordx4 v[116:117], v[104:107], off offset:2048
	s_nop 1
	v_pk_mul_f32 v[104:105], v[114:115], v[110:111]
	v_pk_mul_f32 v[106:107], v[120:121], v[122:123]
	global_store_dwordx4 v[116:117], v[104:107], off offset:2064
	s_and_saveexec_b64 s[8:9], s[4:5]
	s_cbranch_execz .LBB0_208
	v_mov_b32_e32 v100, v254
	v_lshlrev_b32_e32 v101, 16, v239
	s_mov_b32 s6, 0x41700000
	v_add_f32_e32 v100, v100, v101
	v_cmp_nlt_f32_e32 vcc, s6, v100
	s_and_saveexec_b64 s[10:11], vcc
	s_cbranch_execz .LBB0_207
	v_mul_f32_e32 v100, 0x3fb8aa3b, v100
	v_exp_f32_e32 v101, v100
	s_mov_b32 s6, 0x3a83126f
	v_cmp_ngt_f32_e32 vcc, s6, v101
	s_and_saveexec_b64 s[6:7], vcc
	s_xor_b64 s[12:13], exec, s[6:7]
	s_cbranch_execz .LBB0_231
	v_add_f32_e32 v100, 1.0, v101
	v_cmp_gt_f32_e32 vcc, s58, v100
	s_nop 1
	v_cndmask_b32_e64 v101, 0, 32, vcc
	v_ldexp_f32 v100, v100, v101
	v_log_f32_e32 v100, v100
	s_nop 0
	v_mul_f32_e32 v101, 0x3f317217, v100
	v_fma_f32 v101, v100, s48, -v101
	v_fmac_f32_e32 v101, 0x3377d1cf, v100
	v_fmac_f32_e32 v101, 0x3f317217, v100
	v_cmp_lt_f32_e64 s[6:7], |v100|, s31
	s_nop 1
	v_cndmask_b32_e64 v100, v100, v101, s[6:7]
	v_cndmask_b32_e32 v101, 0, v227, vcc
	v_sub_f32_e32 v100, v100, v101

; __global__ void __launch_bounds__(NTHR, 2) mega(Params P) {
	.amdhsa_kernel _Z4mega6Params
		.amdhsa_group_segment_fixed_size 0
		.amdhsa_private_segment_fixed_size 0
		.amdhsa_kernarg_size 520
		.amdhsa_user_sgpr_count 2
		.amdhsa_user_sgpr_dispatch_ptr 0
		.amdhsa_user_sgpr_queue_ptr 0
		.amdhsa_user_sgpr_kernarg_segment_ptr 1
		.amdhsa_user_sgpr_dispatch_id 0
		.amdhsa_user_sgpr_kernarg_preload_length 0
		.amdhsa_user_sgpr_kernarg_preload_offset 0
		.amdhsa_user_sgpr_private_segment_size 0
		.amdhsa_uses_dynamic_stack 0
		.amdhsa_enable_private_segment 0
		.amdhsa_system_sgpr_workgroup_id_x 1
		.amdhsa_system_sgpr_workgroup_id_y 0
		.amdhsa_system_sgpr_workgroup_id_z 0
		.amdhsa_system_sgpr_workgroup_info 0
		.amdhsa_system_vgpr_workitem_id 2
		.amdhsa_next_free_vgpr 256
		.amdhsa_next_free_sgpr 100
		.amdhsa_accum_offset 256
		.amdhsa_reserve_vcc 1
		.amdhsa_float_round_mode_32 0
		.amdhsa_float_round_mode_16_64 0
		.amdhsa_float_denorm_mode_32 3
		.amdhsa_float_denorm_mode_16_64 3
		.amdhsa_dx10_clamp 1
		.amdhsa_ieee_mode 1
		.amdhsa_fp16_overflow 0
		.amdhsa_tg_split 0
		.amdhsa_exception_fp_ieee_invalid_op 0
		.amdhsa_exception_fp_denorm_src 0
		.amdhsa_exception_fp_ieee_div_zero 0
		.amdhsa_exception_fp_ieee_overflow 0
		.amdhsa_exception_fp_ieee_underflow 0
		.amdhsa_exception_fp_ieee_inexact 0
		.amdhsa_exception_int_div_zero 0
	.end_amdhsa_kernel

; __global__ void __launch_bounds__(NTHR, 2) mega(Params P) {
amdhsa.kernels:
  - .agpr_count:     0
    .args:
      - .offset:         0
        .size:           264
        .value_kind:     by_value
      - .offset:         264
        .size:           4
        .value_kind:     hidden_block_count_x
      - .offset:         268
        .size:           4
        .value_kind:     hidden_block_count_y
      - .offset:         272
        .size:           4
        .value_kind:     hidden_block_count_z
      - .offset:         276
        .size:           2
        .value_kind:     hidden_group_size_x
      - .offset:         278
        .size:           2
        .value_kind:     hidden_group_size_y
      - .offset:         280
        .size:           2
        .value_kind:     hidden_group_size_z
      - .offset:         282
        .size:           2
        .value_kind:     hidden_remainder_x
      - .offset:         284
        .size:           2
        .value_kind:     hidden_remainder_y
      - .offset:         286
        .size:           2
        .value_kind:     hidden_remainder_z
      - .offset:         304
        .size:           8
        .value_kind:     hidden_global_offset_x
      - .offset:         312
        .size:           8
        .value_kind:     hidden_global_offset_y
      - .offset:         320
        .size:           8
        .value_kind:     hidden_global_offset_z
      - .offset:         328
        .size:           2
        .value_kind:     hidden_grid_dims
      - .offset:         352
        .size:           8
        .value_kind:     hidden_multigrid_sync_arg
      - .offset:         384
        .size:           4
        .value_kind:     hidden_dynamic_lds_size
    .group_segment_fixed_size: 0
    .kernarg_segment_align: 8
    .kernarg_segment_size: 520
    .language:       OpenCL C
    .language_version:
      - 2
      - 0
    .max_flat_workgroup_size: 512
    .name:           _Z4mega6Params
    .private_segment_fixed_size: 0
    .sgpr_count:     106
    .sgpr_spill_count: 235
    .symbol:         _Z4mega6Params.kd
    .uniform_work_group_size: 1
    .uses_dynamic_stack: false
    .vgpr_count:     256
    .vgpr_spill_count: 0
    .wavefront_size: 64
